# grid barrier poll loops: s_sleep 2 back-off between system-scope polls
# baseline (speedup 1.0000x reference)
; DEVI void gbar(unsigned* ctr, unsigned& gen, int wv) {
;     ...
;     if (tb == 0) {
;       __hip_atomic_fetch_add(ctr, 1u, __ATOMIC_RELAXED, __HIP_MEMORY_SCOPE_AGENT);
;       const unsigned target = gen * 256u;
;       while (__hip_atomic_load(ctr, __ATOMIC_RELAXED, __HIP_MEMORY_SCOPE_AGENT) < target) { }
;     }
.LBB0_620:
	s_sleep 2
	global_load_dword v0, v33, s[52:53] sc1
	s_waitcnt vmcnt(0)
	v_cmp_gt_u32_e32 vcc, s2, v0
	s_cbranch_vccnz .LBB0_620

; DEVI void gbar(unsigned* ctr, unsigned& gen, int wv) {
;     ...
;     if (tb == 0) {
;       __hip_atomic_fetch_add(ctr, 1u, __ATOMIC_RELAXED, __HIP_MEMORY_SCOPE_AGENT);
;       const unsigned target = gen * 256u;
;       while (__hip_atomic_load(ctr, __ATOMIC_RELAXED, __HIP_MEMORY_SCOPE_AGENT) < target) { }
;     }
.LBB0_2240:
	s_sleep 2
	global_load_dword v0, v33, s[52:53] sc1
	s_waitcnt vmcnt(0)
	v_cmp_gt_u32_e32 vcc, s2, v0
	s_cbranch_vccnz .LBB0_2240
	s_getpc_b64 s[98:99]
